# X5 norm loop: gain vectors register-resident (no reload behind vmcnt(0) after every store)
# speedup vs baseline: 1.0068x; 1.0068x over previous
; DI float bflo(unsigned w) { return __uint_as_float(w << 16); }
; DI float bfhi(unsigned w) { return __uint_as_float(w & 0xffff0000u); }
; template <bool XOUT_BF, int NR>
; DI void norm_rows(const bf16_t* xin, const bf16_t* Rb, const float* gpost, void* xout, const float* gpre, bf16_t* xnb, size_t row0, size_t rstride, int lane) {
;     f32x4 v[NR][4], r[NR][4];
; #pragma unroll
;     for (int q = 0; q < NR; ++q)
; #pragma unroll
;         for (int j = 0; j < 4; ++j) { const size_t off = (row0 + q * rstride) * D + 4 * lane + 256 * j;
;             const u32x2 w = __builtin_nontemporal_load((const u32x2*)(xin + off)); v[q][j] = (f32x4){bflo(w.x), bfhi(w.x), bflo(w.y), bfhi(w.y)};
;             const u32x2 w2 = __builtin_nontemporal_load((const u32x2*)(Rb + off)); r[q][j] = (f32x4){bflo(w2.x), bfhi(w2.x), bflo(w2.y), bfhi(w2.y)}; }
;     float ss[NR], s2[NR];
; #pragma unroll
;     for (int q = 0; q < NR; ++q) { ss[q] = 0.f; s2[q] = 0.f;
; #pragma unroll
;         for (int j = 0; j < 4; ++j) ss[q] += (r[q][j][0] * r[q][j][0] + r[q][j][1] * r[q][j][1]) + (r[q][j][2] * r[q][j][2] + r[q][j][3] * r[q][j][3]); }
; #pragma unroll
;     for (int o = 1; o < 64; o <<= 1)
; #pragma unroll
;         for (int q = 0; q < NR; ++q) ss[q] += __shfl_xor(ss[q], o);
; #pragma unroll
;     for (int q = 0; q < NR; ++q) { const float rinv = __builtin_amdgcn_rsqf(ss[q] * (1.f / 1024.f) + EPS);
; #pragma unroll
;         for (int j = 0; j < 4; ++j) { const size_t off = (row0 + q * rstride) * D + 4 * lane + 256 * j;
;             const f32x4 g = *(const f32x4*)(gpost + 4 * lane + 256 * j); v[q][j] += r[q][j] * rinv * g;
; __global__ void __launch_bounds__(512, 2) mega(Args args) {
;     ...
;         PH_BEGIN
;             for (int m = gw; m < TT; m += 4 * NGW) norm_rows<true, 4>(XB, R, in.g_x_post + l * D, XB, in.g_ff_pre + l * D, XN, (size_t)m, (size_t)NGW, lane);
.LBB0_1364:
	v_readlane_b32 s4, v255, 1
	v_readlane_b32 s5, v255, 2
	s_cmp_ge_i32 s26, s4
	s_cselect_b64 s[4:5], -1, 0
	s_and_b64 s[2:3], s[4:5], s[2:3]
	s_andn2_b64 vcc, exec, s[2:3]
	s_cbranch_vccnz .LBB0_1370
	s_mov_b64 s[2:3], s[84:85]
	s_mov_b32 s4, s83
	v_readlane_b32 s5, v255, 3
	s_mov_b32 s18, s81
	v_readlane_b32 s6, v255, 0
	s_lshl_b32 s4, s6, 3
	s_add_i32 s8, s4, s5
	v_lshl_add_u32 v0, s5, 6, v249
	s_cmpk_gt_i32 s8, 0x7fff
	s_cbranch_scc1 .LBB0_1370
	s_load_dwordx2 s[10:11], s[2:3], 0xa0
	s_load_dwordx2 s[14:15], s[2:3], 0xc8
	s_load_dwordx4 s[4:7], s[2:3], 0xe8
	v_readlane_b32 s12, v255, 15
	v_readlane_b32 s13, v255, 16
	s_lshl_b32 s2, s18, 3
	s_lshl_b64 s[16:17], s[12:13], 2
	s_waitcnt lgkmcnt(0)
	s_add_u32 s10, s10, s16
	s_addc_u32 s11, s11, s17
	s_ashr_i32 s3, s2, 31
	s_cmp_lg_u64 s[4:5], 0
	v_lshlrev_b32_e32 v1, 4, v0
	s_cselect_b64 s[12:13], -1, 0
	s_add_u32 s14, s14, s16
	v_and_b32_e32 v176, 0x3f0, v1
	s_addc_u32 s15, s15, s17
	v_lshl_add_u64 v[6:7], s[14:15], 0, v[176:177]
	s_lshl_b32 s14, s18, 5
	s_ashr_i32 s9, s8, 31
	s_ashr_i32 s15, s14, 31
	s_lshl_b64 s[20:21], s[8:9], 11
	v_lshlrev_b32_e32 v0, 3, v0
	s_lshl_b64 s[16:17], s[14:15], 11
	s_lshl_b64 s[22:23], s[2:3], 12
	v_and_b32_e32 v2, 0x1f8, v0
	s_add_u32 s15, s22, s20
	v_or_b32_e32 v0, s20, v2
	v_mov_b32_e32 v1, s21
	s_addc_u32 s19, s23, s21
	s_mul_i32 s18, s18, 0xc000
	v_lshl_add_u64 v[8:9], s[6:7], 0, v[0:1]
	v_lshl_add_u64 v[10:11], s[4:5], 0, v[0:1]
	v_or_b32_e32 v0, s15, v2
	s_mul_hi_i32 s15, s2, 0x1800
	s_add_u32 s18, s18, s20
	s_addc_u32 s15, s15, s21
	s_add_u32 s2, s2, s8
	s_addc_u32 s3, s3, s9
	v_mov_b32_e32 v1, s19
	s_lshl_b64 s[2:3], s[2:3], 11
	v_lshl_add_u64 v[12:13], s[6:7], 0, v[0:1]
	v_lshl_add_u64 v[14:15], s[4:5], 0, v[0:1]
	v_or_b32_e32 v0, s18, v2
	v_mov_b32_e32 v1, s15
	v_or_b32_e32 v2, s2, v2
	v_mov_b32_e32 v3, s3
	v_lshl_add_u64 v[4:5], s[10:11], 0, v[176:177]
	global_load_dwordx4 v[140:143], v[4:5], off
	global_load_dwordx4 v[144:147], v[4:5], off offset:1024
	global_load_dwordx4 v[148:151], v[4:5], off offset:2048
	global_load_dwordx4 v[152:155], v[4:5], off offset:3072
	global_load_dwordx4 v[156:159], v[6:7], off
	global_load_dwordx4 v[160:163], v[6:7], off offset:1024
	global_load_dwordx4 v[164:167], v[6:7], off offset:2048
	global_load_dwordx4 v[168:171], v[6:7], off offset:3072
	s_mov_b64 s[10:11], 0
	v_lshl_add_u64 v[16:17], s[6:7], 0, v[0:1]
	v_lshl_add_u64 v[18:19], s[6:7], 0, v[2:3]
	v_lshl_add_u64 v[20:21], s[4:5], 0, v[0:1]
	v_lshl_add_u64 v[22:23], s[4:5], 0, v[2:3]
	s_branch .LBB0_1368

; DI float bflo(unsigned w) { return __uint_as_float(w << 16); }
; DI float bfhi(unsigned w) { return __uint_as_float(w & 0xffff0000u); }
; template <bool XOUT_BF, int NR>
; DI void norm_rows(const bf16_t* xin, const bf16_t* Rb, const float* gpost, void* xout, const float* gpre, bf16_t* xnb, size_t row0, size_t rstride, int lane) {
;     f32x4 v[NR][4], r[NR][4];
; #pragma unroll
;     for (int q = 0; q < NR; ++q)
; #pragma unroll
;         for (int j = 0; j < 4; ++j) { const size_t off = (row0 + q * rstride) * D + 4 * lane + 256 * j;
;             const u32x2 w = __builtin_nontemporal_load((const u32x2*)(xin + off)); v[q][j] = (f32x4){bflo(w.x), bfhi(w.x), bflo(w.y), bfhi(w.y)};
;             const u32x2 w2 = __builtin_nontemporal_load((const u32x2*)(Rb + off)); r[q][j] = (f32x4){bflo(w2.x), bfhi(w2.x), bflo(w2.y), bfhi(w2.y)}; }
;     float ss[NR], s2[NR];
; #pragma unroll
;     for (int q = 0; q < NR; ++q) { ss[q] = 0.f; s2[q] = 0.f;
; #pragma unroll
;         for (int j = 0; j < 4; ++j) ss[q] += (r[q][j][0] * r[q][j][0] + r[q][j][1] * r[q][j][1]) + (r[q][j][2] * r[q][j][2] + r[q][j][3] * r[q][j][3]); }
; #pragma unroll
;     for (int o = 1; o < 64; o <<= 1)
; #pragma unroll
;         for (int q = 0; q < NR; ++q) ss[q] += __shfl_xor(ss[q], o);
.LBB0_1368:
	s_waitcnt vmcnt(16)
	v_lshl_add_u64 v[28:29], v[8:9], 0, s[10:11]
	v_add_co_u32_e32 v24, vcc, 0x3d00000, v28
	s_mov_b64 s[2:3], vcc
	v_add_co_u32_e32 v0, vcc, 0x7d00000, v28
	v_lshl_add_u64 v[26:27], v[18:19], 0, s[10:11]
	s_nop 0
	v_addc_co_u32_e32 v1, vcc, 0, v29, vcc
	global_load_dwordx2 v[36:37], v[0:1], off offset:1536 nt
	global_load_dwordx2 v[34:35], v[0:1], off nt
	global_load_dwordx2 v[32:33], v[0:1], off offset:512 nt
	global_load_dwordx2 v[30:31], v[0:1], off offset:1024 nt
	s_mov_b32 s4, 0x3d00000
	v_add_co_u32_e32 v62, vcc, s4, v26
	s_mov_b32 s5, 0x7d00000
	s_nop 0
	v_addc_co_u32_e32 v63, vcc, 0, v27, vcc
	v_add_co_u32_e32 v46, vcc, s5, v26
	v_lshl_add_u64 v[38:39], v[12:13], 0, s[10:11]
	s_nop 0
	v_addc_co_u32_e32 v47, vcc, 0, v27, vcc
	v_add_co_u32_e32 v40, vcc, s4, v38
	v_lshl_add_u64 v[42:43], v[16:17], 0, s[10:11]
	s_nop 0
	v_addc_co_u32_e32 v41, vcc, 0, v39, vcc
	v_add_co_u32_e32 v48, vcc, s5, v38
	s_nop 0
	v_addc_co_u32_e32 v49, vcc, 0, v39, vcc
	v_add_co_u32_e32 v26, vcc, s4, v42
	s_waitcnt vmcnt(0)
	v_mov_b32_e32 v0, v140
	v_mov_b32_e32 v1, v141
	v_mov_b32_e32 v2, v142
	v_mov_b32_e32 v3, v143
	v_lshlrev_b32_e32 v81, 16, v36
	v_addc_co_u32_e32 v27, vcc, 0, v43, vcc
	v_add_co_u32_e32 v56, vcc, s5, v42
	v_and_b32_e32 v99, 0xffff0000, v34
	s_nop 0
	v_addc_co_u32_e32 v57, vcc, 0, v43, vcc
	v_addc_co_u32_e64 v25, vcc, 0, v29, s[2:3]
	global_load_dwordx2 v[106:107], v[24:25], off nt
	global_load_dwordx2 v[74:75], v[62:63], off nt
	global_load_dwordx2 v[38:39], v[62:63], off offset:512 nt
	global_load_dwordx2 v[44:45], v[62:63], off offset:1024 nt
	global_load_dwordx2 v[52:53], v[62:63], off offset:1536 nt
	v_and_b32_e32 v101, 0xffff0000, v35
	v_lshlrev_b32_e32 v98, 16, v34
	v_lshlrev_b32_e32 v100, 16, v35
	v_lshlrev_b32_e32 v94, 16, v32
	v_and_b32_e32 v93, 0xffff0000, v33
	v_and_b32_e32 v92, 0xffff0000, v32
	v_mul_f32_e32 v28, v101, v101
	v_mul_f32_e32 v32, v99, v99
	v_mov_b32_e32 v29, v81
	v_lshlrev_b32_e32 v95, 16, v33
	v_lshlrev_b32_e32 v34, 16, v30
	v_and_b32_e32 v35, 0xffff0000, v30
	v_lshlrev_b32_e32 v88, 16, v31
	v_and_b32_e32 v89, 0xffff0000, v31
	v_pk_mul_f32 v[30:31], v[92:93], v[92:93]
	v_pk_fma_f32 v[50:51], v[100:101], v[100:101], v[28:29] op_sel_hi:[1,1,0]
	v_pk_fma_f32 v[32:33], v[98:99], v[98:99], v[32:33] op_sel_hi:[1,1,0]
	v_and_b32_e32 v79, 0xffff0000, v36
	v_lshlrev_b32_e32 v76, 16, v37
	v_and_b32_e32 v77, 0xffff0000, v37
	v_mul_f32_e32 v36, v35, v35
	v_mul_f32_e32 v42, v89, v89
	v_pk_fma_f32 v[30:31], v[94:95], v[94:95], v[30:31]
	v_mov_b32_e32 v80, v32
	v_mov_b32_e32 v28, v50
	v_mul_f32_e32 v54, v79, v79
	v_mul_f32_e32 v55, v76, v76
	v_mul_f32_e32 v58, v77, v77
	v_pk_fma_f32 v[36:37], v[34:35], v[34:35], v[36:37] op_sel_hi:[1,1,0]
	v_pk_fma_f32 v[42:43], v[88:89], v[88:89], v[42:43] op_sel_hi:[1,1,0]
	v_pk_add_f32 v[32:33], v[32:33], v[50:51]
	v_pk_add_f32 v[30:31], v[30:31], v[30:31] op_sel:[0,1] op_sel_hi:[1,0]
	v_pk_mul_f32 v[28:29], v[80:81], v[28:29]
	v_mov_b32_e32 v37, v55
	v_mov_b32_e32 v43, v58
	v_mov_b32_e32 v31, v54
	v_mov_b32_e32 v33, v29
	v_pk_add_f32 v[36:37], v[36:37], v[42:43]
	v_pk_add_f32 v[28:29], v[32:33], v[30:31]
	global_load_dwordx2 v[86:87], v[46:47], off nt
	global_load_dwordx2 v[84:85], v[46:47], off offset:512 nt
	global_load_dwordx2 v[82:83], v[46:47], off offset:1024 nt
	global_load_dwordx2 v[90:91], v[46:47], off offset:1536 nt
	v_pk_add_f32 v[28:29], v[28:29], v[36:37]
	global_load_dwordx2 v[64:65], v[40:41], off nt
	global_load_dwordx2 v[60:61], v[40:41], off offset:512 nt
	global_load_dwordx2 v[58:59], v[40:41], off offset:1024 nt
	global_load_dwordx2 v[54:55], v[40:41], off offset:1536 nt
	v_add_f32_e32 v28, v28, v29
	ds_bpermute_b32 v29, v206, v28
	global_load_dwordx2 v[70:71], v[48:49], off nt
	global_load_dwordx2 v[68:69], v[48:49], off offset:512 nt
	global_load_dwordx2 v[66:67], v[48:49], off offset:1024 nt
	global_load_dwordx2 v[72:73], v[48:49], off offset:1536 nt
	s_andn2_b64 vcc, exec, s[12:13]
	s_waitcnt lgkmcnt(0)
	v_add_f32_e32 v28, v28, v29
	ds_bpermute_b32 v29, v207, v28
	s_waitcnt lgkmcnt(0)
	v_add_f32_e32 v28, v28, v29
	ds_bpermute_b32 v29, v208, v28
	s_waitcnt lgkmcnt(0)
	v_add_f32_e32 v32, v28, v29
	ds_bpermute_b32 v33, v209, v32
	global_load_dwordx2 v[42:43], v[26:27], off nt
	global_load_dwordx2 v[36:37], v[26:27], off offset:512 nt
	global_load_dwordx2 v[30:31], v[26:27], off offset:1024 nt
	global_load_dwordx2 v[28:29], v[26:27], off offset:1536 nt
	global_load_dwordx2 v[50:51], v[56:57], off nt
	global_load_dwordx2 v[48:49], v[56:57], off offset:512 nt
	global_load_dwordx2 v[46:47], v[56:57], off offset:1024 nt
	s_nop 0
	global_load_dwordx2 v[56:57], v[56:57], off offset:1536 nt
	s_nop 0
	global_load_dwordx2 v[104:105], v[24:25], off offset:512 nt
	global_load_dwordx2 v[102:103], v[24:25], off offset:1024 nt
	global_load_dwordx2 v[96:97], v[24:25], off offset:1536 nt
	s_waitcnt lgkmcnt(0)
	v_add_f32_e32 v32, v32, v33
	ds_bpermute_b32 v33, v210, v32
	s_waitcnt lgkmcnt(0)
	v_add_f32_e32 v33, v32, v33
	ds_bpermute_b32 v78, v211, v33
	s_waitcnt vmcnt(0)
	v_lshlrev_b32_e32 v32, 16, v106
	s_waitcnt lgkmcnt(0)
; DI unsigned cvt_pk_bf16(float lo, float hi) { const f32x2 v = {lo, hi}; return __builtin_bit_cast(unsigned, __builtin_convertvector(v, bf16x2_t)); }
; DI float bflo(unsigned w) { return __uint_as_float(w << 16); }
; DI float bfhi(unsigned w) { return __uint_as_float(w & 0xffff0000u); }
; template <bool XOUT_BF, int NR>
; DI void norm_rows(const bf16_t* xin, const bf16_t* Rb, const float* gpost, void* xout, const float* gpre, bf16_t* xnb, size_t row0, size_t rstride, int lane) {
;     ...
;     for (int q = 0; q < NR; ++q) { const float rinv = __builtin_amdgcn_rsqf(ss[q] * (1.f / 1024.f) + EPS);
; #pragma unroll
;         for (int j = 0; j < 4; ++j) { const size_t off = (row0 + q * rstride) * D + 4 * lane + 256 * j;
;             const f32x4 g = *(const f32x4*)(gpost + 4 * lane + 256 * j); v[q][j] += r[q][j] * rinv * g;
;             if (XOUT_BF) { u32x2 w; w.x = cvt_pk_bf16(v[q][j][0], v[q][j][1]); w.y = cvt_pk_bf16(v[q][j][2], v[q][j][3]); __builtin_nontemporal_store(w, (u32x2*)((bf16_t*)xout + off));
;                            v[q][j] = (f32x4){bflo(w.x), bfhi(w.x), bflo(w.y), bfhi(w.y)}; }
;             else *(f32x4*)((float*)xout + off) = v[q][j];
;             s2[q] += (v[q][j][0] * v[q][j][0] + v[q][j][1] * v[q][j][1]) + (v[q][j][2] * v[q][j][2] + v[q][j][3] * v[q][j][3]); } }
;     if (xnb) {
; #pragma unroll
;         for (int o = 1; o < 64; o <<= 1)
; #pragma unroll
;             for (int q = 0; q < NR; ++q) s2[q] += __shfl_xor(s2[q], o);
	v_add_f32_e32 v33, v33, v78
	v_fmamk_f32 v33, v33, 0x3a800000, v217
	v_rsq_f32_e32 v80, v33
	v_and_b32_e32 v33, 0xffff0000, v106
	v_lshlrev_b32_e32 v106, 16, v107
	v_and_b32_e32 v107, 0xffff0000, v107
	v_pk_mul_f32 v[98:99], v[80:81], v[98:99] op_sel_hi:[0,1]
	v_pk_mul_f32 v[100:101], v[80:81], v[100:101] op_sel_hi:[0,1]
	v_pk_fma_f32 v[2:3], v[2:3], v[100:101], v[106:107]
	v_pk_fma_f32 v[0:1], v[0:1], v[98:99], v[32:33]
	v_cvt_pk_bf16_f32 v33, v2, v3
	v_cvt_pk_bf16_f32 v32, v0, v1
	global_store_dwordx2 v[24:25], v[32:33], off nt
	v_pk_mul_f32 v[34:35], v[80:81], v[34:35] op_sel_hi:[0,1]
	v_pk_mul_f32 v[88:89], v[80:81], v[88:89] op_sel_hi:[0,1]
	v_mov_b32_e32 v78, v81
	v_pk_mul_f32 v[78:79], v[80:81], v[78:79] op_sel_hi:[0,1]
	v_pk_mul_f32 v[76:77], v[80:81], v[76:77] op_sel_hi:[0,1]
	s_nop 0
	v_mov_b32_e32 v0, v144
	v_mov_b32_e32 v1, v145
	v_mov_b32_e32 v2, v146
	v_mov_b32_e32 v3, v147
	v_lshlrev_b32_e32 v98, 16, v104
	v_and_b32_e32 v99, 0xffff0000, v104
	v_lshlrev_b32_e32 v100, 16, v105
	v_and_b32_e32 v101, 0xffff0000, v105
	v_mov_b32_e32 v104, v94
	v_mov_b32_e32 v105, v92
	v_mov_b32_e32 v92, v95
	v_pk_mul_f32 v[94:95], v[80:81], v[104:105] op_sel_hi:[0,1]
	v_pk_mul_f32 v[92:93], v[80:81], v[92:93] op_sel_hi:[0,1]
	v_and_b32_e32 v81, 0xffff0000, v83
	v_lshlrev_b32_e32 v80, 16, v83
	s_nop 0
	v_pk_fma_f32 v[2:3], v[2:3], v[92:93], v[100:101]
	v_pk_fma_f32 v[0:1], v[0:1], v[94:95], v[98:99]
	v_lshlrev_b32_e32 v98, 16, v103
	v_cvt_pk_bf16_f32 v0, v0, v1
	v_cvt_pk_bf16_f32 v1, v2, v3
	global_store_dwordx2 v[24:25], v[0:1], off offset:512 nt
	v_lshlrev_b32_e32 v2, 16, v102
	v_and_b32_e32 v3, 0xffff0000, v102
	v_and_b32_e32 v99, 0xffff0000, v103
	s_nop 0
	v_mov_b32_e32 v92, v148
	v_mov_b32_e32 v93, v149
	v_mov_b32_e32 v94, v150
	v_mov_b32_e32 v95, v151
	v_pk_fma_f32 v[88:89], v[94:95], v[88:89], v[98:99]
	v_pk_fma_f32 v[2:3], v[92:93], v[34:35], v[2:3]
	v_lshlrev_b32_e32 v34, 16, v96
	v_cvt_pk_bf16_f32 v2, v2, v3
	v_cvt_pk_bf16_f32 v3, v88, v89
	global_store_dwordx2 v[24:25], v[2:3], off offset:1024 nt
	v_and_b32_e32 v35, 0xffff0000, v96
	v_lshlrev_b32_e32 v96, 16, v97
	v_and_b32_e32 v97, 0xffff0000, v97
	v_lshlrev_b32_e32 v95, 16, v90
	v_and_b32_e32 v93, 0xffff0000, v90
	v_lshlrev_b32_e32 v88, 16, v91
	v_and_b32_e32 v89, 0xffff0000, v91
	v_lshlrev_b32_e32 v90, 16, v86
	v_and_b32_e32 v91, 0xffff0000, v86
	v_lshlrev_b32_e32 v86, 16, v87
	v_and_b32_e32 v87, 0xffff0000, v87
	v_mul_f32_e32 v94, v81, v81
	v_pk_fma_f32 v[106:107], v[80:81], v[80:81], v[94:95] op_sel_hi:[1,1,0]
	v_mul_f32_e32 v108, v93, v93
	v_mul_f32_e32 v109, v88, v88
	v_mul_f32_e32 v110, v89, v89
	v_mov_b32_e32 v107, v110
	s_nop 0
	v_mov_b32_e32 v98, v152
	v_mov_b32_e32 v99, v153
	v_mov_b32_e32 v100, v154
	v_mov_b32_e32 v101, v155
	v_pk_fma_f32 v[76:77], v[76:77], v[100:101], v[96:97]
	v_pk_fma_f32 v[34:35], v[78:79], v[98:99], v[34:35]
	v_lshlrev_b32_e32 v97, 16, v85
	v_cvt_pk_bf16_f32 v34, v34, v35
	v_cvt_pk_bf16_f32 v35, v76, v77
	global_store_dwordx2 v[24:25], v[34:35], off offset:1536 nt
	v_lshlrev_b32_e32 v96, 16, v84
	v_and_b32_e32 v85, 0xffff0000, v85
	v_and_b32_e32 v84, 0xffff0000, v84
	v_lshlrev_b32_e32 v78, 16, v82
	v_and_b32_e32 v79, 0xffff0000, v82
	v_mul_f32_e32 v24, v87, v87
	v_mul_f32_e32 v82, v91, v91
	v_mov_b32_e32 v25, v95
	v_pk_mul_f32 v[76:77], v[84:85], v[84:85]
	v_pk_fma_f32 v[102:103], v[86:87], v[86:87], v[24:25] op_sel_hi:[1,1,0]
	v_pk_fma_f32 v[82:83], v[90:91], v[90:91], v[82:83] op_sel_hi:[1,1,0]
	v_mul_f32_e32 v92, v79, v79
	v_pk_fma_f32 v[76:77], v[96:97], v[96:97], v[76:77]
	v_mov_b32_e32 v94, v82
	v_mov_b32_e32 v24, v102
	v_pk_fma_f32 v[104:105], v[78:79], v[78:79], v[92:93] op_sel_hi:[1,1,0]
	v_pk_add_f32 v[82:83], v[82:83], v[102:103]
	v_pk_add_f32 v[76:77], v[76:77], v[76:77] op_sel:[0,1] op_sel_hi:[1,0]
	v_pk_mul_f32 v[24:25], v[94:95], v[24:25]
	v_mov_b32_e32 v105, v109
	v_mov_b32_e32 v77, v108
	v_mov_b32_e32 v83, v25
	v_pk_add_f32 v[102:103], v[104:105], v[106:107]
	v_pk_add_f32 v[24:25], v[82:83], v[76:77]
	v_mov_b32_e32 v92, v95
	v_pk_add_f32 v[24:25], v[24:25], v[102:103]
	s_nop 0
	v_add_f32_e32 v24, v24, v25
	ds_bpermute_b32 v25, v206, v24
	s_waitcnt lgkmcnt(0)
	v_add_f32_e32 v24, v24, v25
	ds_bpermute_b32 v25, v207, v24
	s_waitcnt lgkmcnt(0)
	v_add_f32_e32 v24, v24, v25
	ds_bpermute_b32 v25, v208, v24
	s_waitcnt lgkmcnt(0)
	v_add_f32_e32 v24, v24, v25
	ds_bpermute_b32 v25, v209, v24
	s_waitcnt lgkmcnt(0)
	v_add_f32_e32 v24, v24, v25
	ds_bpermute_b32 v25, v210, v24
	s_waitcnt lgkmcnt(0)
	v_add_f32_e32 v25, v24, v25
	ds_bpermute_b32 v76, v211, v25
	v_lshlrev_b32_e32 v24, 16, v74
	s_waitcnt lgkmcnt(0)
; DI unsigned cvt_pk_bf16(float lo, float hi) { const f32x2 v = {lo, hi}; return __builtin_bit_cast(unsigned, __builtin_convertvector(v, bf16x2_t)); }
; DI float bflo(unsigned w) { return __uint_as_float(w << 16); }
; DI float bfhi(unsigned w) { return __uint_as_float(w & 0xffff0000u); }
; template <bool XOUT_BF, int NR>
; DI void norm_rows(const bf16_t* xin, const bf16_t* Rb, const float* gpost, void* xout, const float* gpre, bf16_t* xnb, size_t row0, size_t rstride, int lane) {
;     ...
;     for (int q = 0; q < NR; ++q) { const float rinv = __builtin_amdgcn_rsqf(ss[q] * (1.f / 1024.f) + EPS);
; #pragma unroll
;         for (int j = 0; j < 4; ++j) { const size_t off = (row0 + q * rstride) * D + 4 * lane + 256 * j;
;             const f32x4 g = *(const f32x4*)(gpost + 4 * lane + 256 * j); v[q][j] += r[q][j] * rinv * g;
;             if (XOUT_BF) { u32x2 w; w.x = cvt_pk_bf16(v[q][j][0], v[q][j][1]); w.y = cvt_pk_bf16(v[q][j][2], v[q][j][3]); __builtin_nontemporal_store(w, (u32x2*)((bf16_t*)xout + off));
;                            v[q][j] = (f32x4){bflo(w.x), bfhi(w.x), bflo(w.y), bfhi(w.y)}; }
;             else *(f32x4*)((float*)xout + off) = v[q][j];
;             s2[q] += (v[q][j][0] * v[q][j][0] + v[q][j][1] * v[q][j][1]) + (v[q][j][2] * v[q][j][2] + v[q][j][3] * v[q][j][3]); } }
;     if (xnb) {
; #pragma unroll
;         for (int o = 1; o < 64; o <<= 1)
; #pragma unroll
;             for (int q = 0; q < NR; ++q) s2[q] += __shfl_xor(s2[q], o);
	v_add_f32_e32 v25, v25, v76
	v_fmamk_f32 v25, v25, 0x3a800000, v217
	v_rsq_f32_e32 v76, v25
	v_and_b32_e32 v25, 0xffff0000, v74
	v_lshlrev_b32_e32 v74, 16, v75
	v_and_b32_e32 v75, 0xffff0000, v75
	v_pk_mul_f32 v[82:83], v[76:77], v[90:91] op_sel_hi:[0,1]
	v_pk_mul_f32 v[86:87], v[76:77], v[86:87] op_sel_hi:[0,1]
	v_pk_mul_f32 v[78:79], v[76:77], v[78:79] op_sel_hi:[0,1]
	v_pk_mul_f32 v[80:81], v[76:77], v[80:81] op_sel_hi:[0,1]
	s_nop 0
	v_mov_b32_e32 v98, v140
	v_mov_b32_e32 v99, v141
	v_mov_b32_e32 v100, v142
	v_mov_b32_e32 v101, v143
	v_pk_fma_f32 v[74:75], v[86:87], v[100:101], v[74:75]
	v_pk_fma_f32 v[24:25], v[82:83], v[98:99], v[24:25]
	v_mov_b32_e32 v82, v96
	v_cvt_pk_bf16_f32 v24, v24, v25
	v_cvt_pk_bf16_f32 v25, v74, v75
	global_store_dwordx2 v[62:63], v[24:25], off nt
	v_mov_b32_e32 v83, v84
	v_mov_b32_e32 v84, v97
	v_lshlrev_b32_e32 v74, 16, v38
	v_and_b32_e32 v75, 0xffff0000, v38
	v_lshlrev_b32_e32 v38, 16, v39
	v_and_b32_e32 v39, 0xffff0000, v39
	v_pk_mul_f32 v[82:83], v[76:77], v[82:83] op_sel_hi:[0,1]
	v_pk_mul_f32 v[84:85], v[76:77], v[84:85] op_sel_hi:[0,1]
	v_lshlrev_b32_e32 v77, 16, v72
	v_lshlrev_b32_e32 v86, 16, v52
	v_and_b32_e32 v87, 0xffff0000, v52
	v_lshlrev_b32_e32 v52, 16, v53
	v_and_b32_e32 v53, 0xffff0000, v53
	v_pk_mul_f32 v[90:91], v[76:77], v[92:93] op_sel_hi:[0,1]
	v_pk_mul_f32 v[88:89], v[76:77], v[88:89] op_sel_hi:[0,1]
	s_nop 0
	v_mov_b32_e32 v98, v144
	v_mov_b32_e32 v99, v145
	v_mov_b32_e32 v100, v146
	v_mov_b32_e32 v101, v147
	v_pk_fma_f32 v[84:85], v[84:85], v[100:101], v[38:39]
	v_pk_fma_f32 v[38:39], v[82:83], v[98:99], v[74:75]
	v_lshlrev_b32_e32 v74, 16, v44
	v_cvt_pk_bf16_f32 v38, v38, v39
	v_cvt_pk_bf16_f32 v39, v84, v85
	global_store_dwordx2 v[62:63], v[38:39], off offset:512 nt
	v_and_b32_e32 v75, 0xffff0000, v44
	v_lshlrev_b32_e32 v44, 16, v45
	v_and_b32_e32 v45, 0xffff0000, v45
	s_nop 0
	v_mov_b32_e32 v82, v148
	v_mov_b32_e32 v83, v149
	v_mov_b32_e32 v84, v150
	v_mov_b32_e32 v85, v151
	v_pk_fma_f32 v[80:81], v[80:81], v[84:85], v[44:45]
	v_pk_fma_f32 v[44:45], v[78:79], v[82:83], v[74:75]
	v_and_b32_e32 v79, 0xffff0000, v70
	v_cvt_pk_bf16_f32 v44, v44, v45
	v_cvt_pk_bf16_f32 v45, v80, v81
	global_store_dwordx2 v[62:63], v[44:45], off offset:1024 nt
	v_and_b32_e32 v81, 0xffff0000, v71
	v_and_b32_e32 v75, 0xffff0000, v72
	v_lshlrev_b32_e32 v78, 16, v70
	v_lshlrev_b32_e32 v80, 16, v71
	v_mul_f32_e32 v74, v79, v79
	v_lshlrev_b32_e32 v70, 16, v67
	v_and_b32_e32 v71, 0xffff0000, v67
	v_pk_fma_f32 v[94:95], v[78:79], v[78:79], v[74:75] op_sel_hi:[1,1,0]
	v_lshlrev_b32_e32 v72, 16, v73
	v_and_b32_e32 v73, 0xffff0000, v73
	v_mul_f32_e32 v98, v75, v75
	v_mul_f32_e32 v99, v72, v72
	v_mul_f32_e32 v100, v73, v73
	v_mov_b32_e32 v74, v77
	s_nop 0
	v_mov_b32_e32 v82, v152
	v_mov_b32_e32 v83, v153
	v_mov_b32_e32 v84, v154
	v_mov_b32_e32 v85, v155
	v_pk_fma_f32 v[84:85], v[88:89], v[84:85], v[52:53]
	v_pk_fma_f32 v[52:53], v[90:91], v[82:83], v[86:87]
	v_and_b32_e32 v83, 0xffff0000, v69
	v_cvt_pk_bf16_f32 v52, v52, v53
	v_cvt_pk_bf16_f32 v53, v84, v85
	global_store_dwordx2 v[62:63], v[52:53], off offset:1536 nt
	v_lshlrev_b32_e32 v85, 16, v69
	v_and_b32_e32 v82, 0xffff0000, v68
	v_and_b32_e32 v69, 0xffff0000, v66
	v_mul_f32_e32 v62, v81, v81
	v_mov_b32_e32 v63, v77
	v_lshlrev_b32_e32 v84, 16, v68
	v_lshlrev_b32_e32 v68, 16, v66
	v_pk_mul_f32 v[66:67], v[82:83], v[82:83]
	v_mul_f32_e32 v76, v69, v69
	v_pk_fma_f32 v[92:93], v[80:81], v[80:81], v[62:63] op_sel_hi:[1,1,0]
	v_mul_f32_e32 v90, v71, v71
	v_pk_fma_f32 v[66:67], v[84:85], v[84:85], v[66:67]
	v_pk_fma_f32 v[96:97], v[68:69], v[68:69], v[76:77] op_sel_hi:[1,1,0]
	v_mov_b32_e32 v76, v94
	v_mov_b32_e32 v62, v92
	v_pk_fma_f32 v[90:91], v[70:71], v[70:71], v[90:91] op_sel_hi:[1,1,0]
	v_pk_add_f32 v[92:93], v[94:95], v[92:93]
	v_pk_add_f32 v[66:67], v[66:67], v[66:67] op_sel:[0,1] op_sel_hi:[1,0]
	v_pk_mul_f32 v[62:63], v[76:77], v[62:63]
	v_mov_b32_e32 v97, v99
	v_mov_b32_e32 v91, v100
	v_mov_b32_e32 v67, v98
	v_mov_b32_e32 v93, v63
	v_pk_add_f32 v[90:91], v[96:97], v[90:91]
	v_pk_add_f32 v[62:63], v[92:93], v[66:67]
	s_nop 0
	v_pk_add_f32 v[62:63], v[62:63], v[90:91]
	s_nop 0
	v_add_f32_e32 v62, v62, v63
	ds_bpermute_b32 v63, v206, v62
	s_waitcnt lgkmcnt(0)
	v_add_f32_e32 v62, v62, v63
	ds_bpermute_b32 v63, v207, v62
	s_waitcnt lgkmcnt(0)
	v_add_f32_e32 v62, v62, v63
	ds_bpermute_b32 v63, v208, v62
	s_waitcnt lgkmcnt(0)
	v_add_f32_e32 v62, v62, v63
	ds_bpermute_b32 v63, v209, v62
	s_waitcnt lgkmcnt(0)
	v_add_f32_e32 v62, v62, v63
	ds_bpermute_b32 v63, v210, v62
	s_waitcnt lgkmcnt(0)
	v_add_f32_e32 v63, v62, v63
	ds_bpermute_b32 v66, v211, v63
	v_lshlrev_b32_e32 v62, 16, v64
	s_waitcnt lgkmcnt(0)
; DI unsigned cvt_pk_bf16(float lo, float hi) { const f32x2 v = {lo, hi}; return __builtin_bit_cast(unsigned, __builtin_convertvector(v, bf16x2_t)); }
; DI float bflo(unsigned w) { return __uint_as_float(w << 16); }
; DI float bfhi(unsigned w) { return __uint_as_float(w & 0xffff0000u); }
; template <bool XOUT_BF, int NR>
; DI void norm_rows(const bf16_t* xin, const bf16_t* Rb, const float* gpost, void* xout, const float* gpre, bf16_t* xnb, size_t row0, size_t rstride, int lane) {
;     ...
;     for (int q = 0; q < NR; ++q) { const float rinv = __builtin_amdgcn_rsqf(ss[q] * (1.f / 1024.f) + EPS);
; #pragma unroll
;         for (int j = 0; j < 4; ++j) { const size_t off = (row0 + q * rstride) * D + 4 * lane + 256 * j;
;             const f32x4 g = *(const f32x4*)(gpost + 4 * lane + 256 * j); v[q][j] += r[q][j] * rinv * g;
;             if (XOUT_BF) { u32x2 w; w.x = cvt_pk_bf16(v[q][j][0], v[q][j][1]); w.y = cvt_pk_bf16(v[q][j][2], v[q][j][3]); __builtin_nontemporal_store(w, (u32x2*)((bf16_t*)xout + off));
;                            v[q][j] = (f32x4){bflo(w.x), bfhi(w.x), bflo(w.y), bfhi(w.y)}; }
;             else *(f32x4*)((float*)xout + off) = v[q][j];
;             s2[q] += (v[q][j][0] * v[q][j][0] + v[q][j][1] * v[q][j][1]) + (v[q][j][2] * v[q][j][2] + v[q][j][3] * v[q][j][3]); } }
;     if (xnb) {
; #pragma unroll
;         for (int o = 1; o < 64; o <<= 1)
; #pragma unroll
;             for (int q = 0; q < NR; ++q) s2[q] += __shfl_xor(s2[q], o);
	v_add_f32_e32 v63, v63, v66
	v_fmamk_f32 v63, v63, 0x3a800000, v217
	v_rsq_f32_e32 v66, v63
	v_and_b32_e32 v63, 0xffff0000, v64
	v_lshlrev_b32_e32 v64, 16, v65
	v_and_b32_e32 v65, 0xffff0000, v65
	v_pk_mul_f32 v[78:79], v[66:67], v[78:79] op_sel_hi:[0,1]
	v_pk_mul_f32 v[80:81], v[66:67], v[80:81] op_sel_hi:[0,1]
	v_pk_mul_f32 v[68:69], v[66:67], v[68:69] op_sel_hi:[0,1]
	v_pk_mul_f32 v[70:71], v[66:67], v[70:71] op_sel_hi:[0,1]
	s_nop 0
	v_mov_b32_e32 v86, v140
	v_mov_b32_e32 v87, v141
	v_mov_b32_e32 v88, v142
	v_mov_b32_e32 v89, v143
	v_pk_fma_f32 v[64:65], v[80:81], v[88:89], v[64:65]
	v_pk_fma_f32 v[62:63], v[78:79], v[86:87], v[62:63]
	v_mov_b32_e32 v86, v84
	v_cvt_pk_bf16_f32 v62, v62, v63
	v_cvt_pk_bf16_f32 v63, v64, v65
	global_store_dwordx2 v[40:41], v[62:63], off nt
	v_mov_b32_e32 v87, v82
	v_mov_b32_e32 v82, v85
	v_lshlrev_b32_e32 v64, 16, v60
	v_and_b32_e32 v65, 0xffff0000, v60
	v_lshlrev_b32_e32 v60, 16, v61
	v_and_b32_e32 v61, 0xffff0000, v61
	v_pk_mul_f32 v[84:85], v[66:67], v[86:87] op_sel_hi:[0,1]
	v_pk_mul_f32 v[82:83], v[66:67], v[82:83] op_sel_hi:[0,1]
	v_lshlrev_b32_e32 v67, 16, v56
	v_pk_mul_f32 v[74:75], v[66:67], v[74:75] op_sel_hi:[0,1]
	v_pk_mul_f32 v[72:73], v[66:67], v[72:73] op_sel_hi:[0,1]
	s_nop 0
	v_mov_b32_e32 v78, v144
	v_mov_b32_e32 v79, v145
	v_mov_b32_e32 v80, v146
	v_mov_b32_e32 v81, v147
	v_pk_fma_f32 v[80:81], v[82:83], v[80:81], v[60:61]
	v_pk_fma_f32 v[60:61], v[84:85], v[78:79], v[64:65]
	v_lshlrev_b32_e32 v64, 16, v58
	v_cvt_pk_bf16_f32 v60, v60, v61
	v_cvt_pk_bf16_f32 v61, v80, v81
	global_store_dwordx2 v[40:41], v[60:61], off offset:512 nt
	v_and_b32_e32 v65, 0xffff0000, v58
	v_lshlrev_b32_e32 v58, 16, v59
	v_and_b32_e32 v59, 0xffff0000, v59
	v_lshlrev_b32_e32 v82, 16, v54
	v_and_b32_e32 v83, 0xffff0000, v54
	v_lshlrev_b32_e32 v54, 16, v55
	v_and_b32_e32 v55, 0xffff0000, v55
	s_nop 0
	v_mov_b32_e32 v78, v148
	v_mov_b32_e32 v79, v149
	v_mov_b32_e32 v80, v150
	v_mov_b32_e32 v81, v151
	v_pk_fma_f32 v[70:71], v[70:71], v[80:81], v[58:59]
	v_pk_fma_f32 v[58:59], v[68:69], v[78:79], v[64:65]
	v_and_b32_e32 v69, 0xffff0000, v50
	v_cvt_pk_bf16_f32 v58, v58, v59
	v_cvt_pk_bf16_f32 v59, v70, v71
	global_store_dwordx2 v[40:41], v[58:59], off offset:1024 nt
	v_and_b32_e32 v71, 0xffff0000, v51
	v_and_b32_e32 v65, 0xffff0000, v56
	v_lshlrev_b32_e32 v68, 16, v50
	v_lshlrev_b32_e32 v70, 16, v51
	v_mul_f32_e32 v64, v69, v69
	v_lshlrev_b32_e32 v50, 16, v47
	v_and_b32_e32 v51, 0xffff0000, v47
	v_pk_fma_f32 v[84:85], v[68:69], v[68:69], v[64:65] op_sel_hi:[1,1,0]
	v_lshlrev_b32_e32 v56, 16, v57
	v_and_b32_e32 v57, 0xffff0000, v57
	v_mul_f32_e32 v88, v65, v65
	v_mul_f32_e32 v89, v56, v56
	v_mul_f32_e32 v90, v57, v57
	v_mov_b32_e32 v64, v67
	s_nop 0
	v_mov_b32_e32 v78, v152
	v_mov_b32_e32 v79, v153
	v_mov_b32_e32 v80, v154
	v_mov_b32_e32 v81, v155
	v_pk_fma_f32 v[72:73], v[72:73], v[80:81], v[54:55]
	v_pk_fma_f32 v[54:55], v[74:75], v[78:79], v[82:83]
	v_lshlrev_b32_e32 v75, 16, v49
	v_cvt_pk_bf16_f32 v54, v54, v55
	v_cvt_pk_bf16_f32 v55, v72, v73
	global_store_dwordx2 v[40:41], v[54:55], off offset:1536 nt
	v_and_b32_e32 v73, 0xffff0000, v49
	v_and_b32_e32 v72, 0xffff0000, v48
	v_and_b32_e32 v49, 0xffff0000, v46
	v_mul_f32_e32 v40, v71, v71
	v_mov_b32_e32 v41, v67
	v_lshlrev_b32_e32 v74, 16, v48
	v_lshlrev_b32_e32 v48, 16, v46
	v_pk_mul_f32 v[46:47], v[72:73], v[72:73]
	v_mul_f32_e32 v66, v49, v49
	v_pk_fma_f32 v[82:83], v[70:71], v[70:71], v[40:41] op_sel_hi:[1,1,0]
	v_mul_f32_e32 v80, v51, v51
	v_pk_fma_f32 v[46:47], v[74:75], v[74:75], v[46:47]
	v_pk_fma_f32 v[86:87], v[48:49], v[48:49], v[66:67] op_sel_hi:[1,1,0]
	v_mov_b32_e32 v66, v84
	v_mov_b32_e32 v40, v82
	v_pk_fma_f32 v[80:81], v[50:51], v[50:51], v[80:81] op_sel_hi:[1,1,0]
	v_pk_add_f32 v[82:83], v[84:85], v[82:83]
	v_pk_add_f32 v[46:47], v[46:47], v[46:47] op_sel:[0,1] op_sel_hi:[1,0]
	v_pk_mul_f32 v[40:41], v[66:67], v[40:41]
	v_mov_b32_e32 v87, v89
	v_mov_b32_e32 v81, v90
	v_mov_b32_e32 v47, v88
	v_mov_b32_e32 v83, v41
	v_pk_add_f32 v[80:81], v[86:87], v[80:81]
	v_pk_add_f32 v[40:41], v[82:83], v[46:47]
	s_nop 0
	v_pk_add_f32 v[40:41], v[40:41], v[80:81]
	s_nop 0
	v_add_f32_e32 v40, v40, v41
	ds_bpermute_b32 v41, v206, v40
	s_waitcnt lgkmcnt(0)
	v_add_f32_e32 v40, v40, v41
	ds_bpermute_b32 v41, v207, v40
	s_waitcnt lgkmcnt(0)
	v_add_f32_e32 v40, v40, v41
	ds_bpermute_b32 v41, v208, v40
	s_waitcnt lgkmcnt(0)
	v_add_f32_e32 v40, v40, v41
	ds_bpermute_b32 v41, v209, v40
	s_waitcnt lgkmcnt(0)
	v_add_f32_e32 v40, v40, v41
	ds_bpermute_b32 v41, v210, v40
	s_waitcnt lgkmcnt(0)
	v_add_f32_e32 v41, v40, v41
	ds_bpermute_b32 v46, v211, v41
	v_lshlrev_b32_e32 v40, 16, v42
	s_waitcnt lgkmcnt(0)
; DI unsigned cvt_pk_bf16(float lo, float hi) { const f32x2 v = {lo, hi}; return __builtin_bit_cast(unsigned, __builtin_convertvector(v, bf16x2_t)); }
; DI float bflo(unsigned w) { return __uint_as_float(w << 16); }
; DI float bfhi(unsigned w) { return __uint_as_float(w & 0xffff0000u); }
; template <bool XOUT_BF, int NR>
; DI void norm_rows(const bf16_t* xin, const bf16_t* Rb, const float* gpost, void* xout, const float* gpre, bf16_t* xnb, size_t row0, size_t rstride, int lane) {
;     ...
;     for (int q = 0; q < NR; ++q) { const float rinv = __builtin_amdgcn_rsqf(ss[q] * (1.f / 1024.f) + EPS);
; #pragma unroll
;         for (int j = 0; j < 4; ++j) { const size_t off = (row0 + q * rstride) * D + 4 * lane + 256 * j;
;             const f32x4 g = *(const f32x4*)(gpost + 4 * lane + 256 * j); v[q][j] += r[q][j] * rinv * g;
;             if (XOUT_BF) { u32x2 w; w.x = cvt_pk_bf16(v[q][j][0], v[q][j][1]); w.y = cvt_pk_bf16(v[q][j][2], v[q][j][3]); __builtin_nontemporal_store(w, (u32x2*)((bf16_t*)xout + off));
;                            v[q][j] = (f32x4){bflo(w.x), bfhi(w.x), bflo(w.y), bfhi(w.y)}; }
;             else *(f32x4*)((float*)xout + off) = v[q][j];
;             s2[q] += (v[q][j][0] * v[q][j][0] + v[q][j][1] * v[q][j][1]) + (v[q][j][2] * v[q][j][2] + v[q][j][3] * v[q][j][3]); } }
;     if (xnb) {
; #pragma unroll
;         for (int o = 1; o < 64; o <<= 1)
; #pragma unroll
;             for (int q = 0; q < NR; ++q) s2[q] += __shfl_xor(s2[q], o);
; #pragma unroll
;         for (int q = 0; q < NR; ++q) { const float rinv = __builtin_amdgcn_rsqf(s2[q] * (1.f / 1024.f) + EPS);
; #pragma unroll
;             for (int j = 0; j < 4; ++j) { const size_t off = (row0 + q * rstride) * D + 4 * lane + 256 * j;
;                 const f32x4 g = *(const f32x4*)(gpre + 4 * lane + 256 * j); const f32x4 o = v[q][j] * rinv * g;
;                 u32x2 w; w.x = cvt_pk_bf16(o[0], o[1]); w.y = cvt_pk_bf16(o[2], o[3]); *(u32x2*)(xnb + off) = w; } }
	v_add_f32_e32 v41, v41, v46
	v_fmamk_f32 v41, v41, 0x3a800000, v217
	v_rsq_f32_e32 v46, v41
	v_and_b32_e32 v41, 0xffff0000, v42
	v_lshlrev_b32_e32 v42, 16, v43
	v_and_b32_e32 v43, 0xffff0000, v43
	v_pk_mul_f32 v[68:69], v[46:47], v[68:69] op_sel_hi:[0,1]
	v_pk_mul_f32 v[70:71], v[46:47], v[70:71] op_sel_hi:[0,1]
	v_pk_mul_f32 v[48:49], v[46:47], v[48:49] op_sel_hi:[0,1]
	v_pk_mul_f32 v[50:51], v[46:47], v[50:51] op_sel_hi:[0,1]
	v_pk_mul_f32 v[64:65], v[46:47], v[64:65] op_sel_hi:[0,1]
	s_nop 0
	v_mov_b32_e32 v76, v140
	v_mov_b32_e32 v77, v141
	v_mov_b32_e32 v78, v142
	v_mov_b32_e32 v79, v143
	v_pk_fma_f32 v[42:43], v[70:71], v[78:79], v[42:43]
	v_pk_fma_f32 v[40:41], v[68:69], v[76:77], v[40:41]
	v_mov_b32_e32 v76, v74
	v_cvt_pk_bf16_f32 v40, v40, v41
	v_cvt_pk_bf16_f32 v41, v42, v43
	global_store_dwordx2 v[26:27], v[40:41], off nt
	v_mov_b32_e32 v77, v72
	v_mov_b32_e32 v72, v75
	v_lshlrev_b32_e32 v42, 16, v36
	v_and_b32_e32 v43, 0xffff0000, v36
	v_lshlrev_b32_e32 v36, 16, v37
	v_and_b32_e32 v37, 0xffff0000, v37
	v_pk_mul_f32 v[74:75], v[46:47], v[76:77] op_sel_hi:[0,1]
	v_pk_mul_f32 v[72:73], v[46:47], v[72:73] op_sel_hi:[0,1]
	v_pk_mul_f32 v[46:47], v[46:47], v[56:57] op_sel_hi:[0,1]
	s_nop 0
	v_mov_b32_e32 v68, v144
	v_mov_b32_e32 v69, v145
	v_mov_b32_e32 v70, v146
	v_mov_b32_e32 v71, v147
	v_pk_fma_f32 v[70:71], v[72:73], v[70:71], v[36:37]
	v_pk_fma_f32 v[36:37], v[74:75], v[68:69], v[42:43]
	v_lshlrev_b32_e32 v42, 16, v30
	v_cvt_pk_bf16_f32 v36, v36, v37
	v_cvt_pk_bf16_f32 v37, v70, v71
	global_store_dwordx2 v[26:27], v[36:37], off offset:512 nt
	v_and_b32_e32 v43, 0xffff0000, v30
	v_lshlrev_b32_e32 v30, 16, v31
	v_and_b32_e32 v31, 0xffff0000, v31
	s_nop 0
	v_mov_b32_e32 v68, v148
	v_mov_b32_e32 v69, v149
	v_mov_b32_e32 v70, v150
	v_mov_b32_e32 v71, v151
	v_pk_fma_f32 v[50:51], v[50:51], v[70:71], v[30:31]
	v_pk_fma_f32 v[30:31], v[48:49], v[68:69], v[42:43]
	v_lshlrev_b32_e32 v42, 16, v28
	v_cvt_pk_bf16_f32 v30, v30, v31
	v_cvt_pk_bf16_f32 v31, v50, v51
	global_store_dwordx2 v[26:27], v[30:31], off offset:1024 nt
	v_and_b32_e32 v43, 0xffff0000, v28
	v_lshlrev_b32_e32 v28, 16, v29
	v_and_b32_e32 v29, 0xffff0000, v29
	s_nop 0
	v_mov_b32_e32 v48, v152
	v_mov_b32_e32 v49, v153
	v_mov_b32_e32 v50, v154
	v_mov_b32_e32 v51, v155
	v_pk_fma_f32 v[46:47], v[46:47], v[50:51], v[28:29]
	v_pk_fma_f32 v[28:29], v[64:65], v[48:49], v[42:43]
	s_nop 0
	v_cvt_pk_bf16_f32 v28, v28, v29
	v_cvt_pk_bf16_f32 v29, v46, v47
	global_store_dwordx2 v[26:27], v[28:29], off offset:1536 nt
	s_cbranch_vccnz .LBB0_1367
	v_lshlrev_b32_e32 v27, 16, v33
	v_lshlrev_b32_e32 v26, 16, v32
	v_and_b32_e32 v33, 0xffff0000, v33
	v_and_b32_e32 v32, 0xffff0000, v32
	v_and_b32_e32 v57, 0xffff0000, v1
	v_and_b32_e32 v56, 0xffff0000, v0
	v_lshlrev_b32_e32 v64, 16, v2
	v_and_b32_e32 v65, 0xffff0000, v2
	v_lshlrev_b32_e32 v67, 16, v34
	v_pk_mul_f32 v[42:43], v[32:33], v[32:33]
	v_lshlrev_b32_e32 v51, 16, v1
	v_lshlrev_b32_e32 v50, 16, v0
	v_pk_mul_f32 v[0:1], v[56:57], v[56:57]
	v_mul_f32_e32 v66, v64, v64
	v_mul_f32_e32 v2, v65, v65
	v_lshlrev_b32_e32 v68, 16, v3
	v_and_b32_e32 v69, 0xffff0000, v3
	v_mov_b32_e32 v3, v67
	v_pk_fma_f32 v[42:43], v[26:27], v[26:27], v[42:43]
	v_pk_fma_f32 v[0:1], v[50:51], v[50:51], v[0:1]
	v_and_b32_e32 v71, 0xffff0000, v34
	v_lshlrev_b32_e32 v34, 16, v35
	v_and_b32_e32 v35, 0xffff0000, v35
	v_pk_add_f32 v[2:3], v[66:67], v[2:3]
	v_pk_mul_f32 v[72:73], v[66:67], v[66:67]
	v_mul_f32_e32 v66, v69, v69
	v_mul_f32_e32 v70, v71, v71
	v_mul_f32_e32 v74, v34, v34
	v_mul_f32_e32 v75, v35, v35
	v_mov_b32_e32 v3, v73
	v_pk_fma_f32 v[72:73], v[68:69], v[68:69], v[66:67] op_sel_hi:[1,1,0]
	v_pk_add_f32 v[42:43], v[42:43], v[42:43] op_sel:[0,1] op_sel_hi:[1,0]
	v_pk_add_f32 v[0:1], v[0:1], v[0:1] op_sel:[0,1] op_sel_hi:[1,0]
	v_mov_b32_e32 v73, v70
	v_mov_b32_e32 v43, v74
	v_mov_b32_e32 v1, v75
	v_pk_add_f32 v[2:3], v[2:3], v[72:73]
	v_pk_add_f32 v[0:1], v[42:43], v[0:1]
	v_lshl_add_u64 v[42:43], v[10:11], 0, s[10:11]
	v_pk_add_f32 v[0:1], v[2:3], v[0:1]
	v_mov_b32_e32 v70, v67
	v_add_f32_e32 v0, v0, v1
	ds_bpermute_b32 v1, v206, v0
	s_waitcnt lgkmcnt(0)
	v_add_f32_e32 v0, v0, v1
	ds_bpermute_b32 v1, v207, v0
	s_waitcnt lgkmcnt(0)
	v_add_f32_e32 v0, v0, v1
	ds_bpermute_b32 v1, v208, v0
	s_waitcnt lgkmcnt(0)
	v_add_f32_e32 v0, v0, v1
	ds_bpermute_b32 v1, v209, v0
	s_waitcnt lgkmcnt(0)
	v_add_f32_e32 v0, v0, v1
	ds_bpermute_b32 v1, v210, v0
	s_waitcnt lgkmcnt(0)
	v_add_f32_e32 v0, v0, v1
	ds_bpermute_b32 v1, v211, v0
	s_waitcnt lgkmcnt(0)
; DI unsigned cvt_pk_bf16(float lo, float hi) { const f32x2 v = {lo, hi}; return __builtin_bit_cast(unsigned, __builtin_convertvector(v, bf16x2_t)); }
; template <bool XOUT_BF, int NR>
; DI void norm_rows(const bf16_t* xin, const bf16_t* Rb, const float* gpost, void* xout, const float* gpre, bf16_t* xnb, size_t row0, size_t rstride, int lane) {
;     ...
;     if (xnb) {
; #pragma unroll
;         for (int o = 1; o < 64; o <<= 1)
; #pragma unroll
;             for (int q = 0; q < NR; ++q) s2[q] += __shfl_xor(s2[q], o);
; #pragma unroll
;         for (int q = 0; q < NR; ++q) { const float rinv = __builtin_amdgcn_rsqf(s2[q] * (1.f / 1024.f) + EPS);
; #pragma unroll
;             for (int j = 0; j < 4; ++j) { const size_t off = (row0 + q * rstride) * D + 4 * lane + 256 * j;
;                 const f32x4 g = *(const f32x4*)(gpre + 4 * lane + 256 * j); const f32x4 o = v[q][j] * rinv * g;
;                 u32x2 w; w.x = cvt_pk_bf16(o[0], o[1]); w.y = cvt_pk_bf16(o[2], o[3]); *(u32x2*)(xnb + off) = w; } }
	v_add_f32_e32 v0, v0, v1
	v_fmamk_f32 v0, v0, 0x3a800000, v217
	v_rsq_f32_e32 v66, v0
	v_mov_b32_e32 v0, v26
	v_mov_b32_e32 v1, v32
	v_mov_b32_e32 v32, v27
	v_pk_mul_f32 v[0:1], v[66:67], v[0:1] op_sel_hi:[0,1]
	v_pk_mul_f32 v[2:3], v[66:67], v[32:33] op_sel_hi:[0,1]
	s_nop 0
	v_mov_b32_e32 v46, v156
	v_mov_b32_e32 v47, v157
	v_mov_b32_e32 v48, v158
	v_mov_b32_e32 v49, v159
	v_pk_mul_f32 v[2:3], v[48:49], v[2:3]
	v_pk_mul_f32 v[0:1], v[46:47], v[0:1]
	v_mov_b32_e32 v26, v50
	v_cvt_pk_bf16_f32 v0, v0, v1
	v_cvt_pk_bf16_f32 v1, v2, v3
	global_store_dwordx2 v[42:43], v[0:1], off
	v_mov_b32_e32 v27, v56
	v_mov_b32_e32 v56, v51
	v_pk_mul_f32 v[26:27], v[66:67], v[26:27] op_sel_hi:[0,1]
	v_pk_mul_f32 v[32:33], v[66:67], v[56:57] op_sel_hi:[0,1]
	v_pk_mul_f32 v[46:47], v[70:71], v[66:67] op_sel_hi:[1,0]
	v_pk_mul_f32 v[34:35], v[34:35], v[66:67] op_sel_hi:[1,0]
	v_lshlrev_b32_e32 v48, 16, v53
	v_and_b32_e32 v49, 0xffff0000, v53
	v_mul_f32_e32 v71, v48, v48
	v_mul_f32_e32 v72, v49, v49
	s_nop 0
	v_mov_b32_e32 v0, v160
	v_mov_b32_e32 v1, v161
	v_mov_b32_e32 v2, v162
	v_mov_b32_e32 v3, v163
	v_pk_mul_f32 v[2:3], v[2:3], v[32:33]
	v_pk_mul_f32 v[0:1], v[0:1], v[26:27]
	v_pk_mul_f32 v[26:27], v[64:65], v[66:67] op_sel_hi:[1,0]
	v_cvt_pk_bf16_f32 v0, v0, v1
	v_cvt_pk_bf16_f32 v1, v2, v3
	global_store_dwordx2 v[42:43], v[0:1], off offset:512
	v_pk_mul_f32 v[32:33], v[68:69], v[66:67] op_sel_hi:[1,0]
	s_nop 0
	v_mov_b32_e32 v0, v164
	v_mov_b32_e32 v1, v165
	v_mov_b32_e32 v2, v166
	v_mov_b32_e32 v3, v167
	v_pk_mul_f32 v[0:1], v[0:1], v[26:27]
	v_pk_mul_f32 v[2:3], v[2:3], v[32:33]
	v_cvt_pk_bf16_f32 v0, v0, v1
	v_cvt_pk_bf16_f32 v1, v2, v3
	global_store_dwordx2 v[42:43], v[0:1], off offset:1024
	v_lshlrev_b32_e32 v26, 16, v24
	v_and_b32_e32 v27, 0xffff0000, v24
	v_lshlrev_b32_e32 v24, 16, v25
	v_and_b32_e32 v25, 0xffff0000, v25
	v_lshlrev_b32_e32 v33, 16, v39
	v_lshlrev_b32_e32 v32, 16, v38
	v_and_b32_e32 v39, 0xffff0000, v39
	v_and_b32_e32 v38, 0xffff0000, v38
	v_pk_mul_f32 v[50:51], v[38:39], v[38:39]
	s_nop 0
	v_mov_b32_e32 v0, v168
	v_mov_b32_e32 v1, v169
	v_mov_b32_e32 v2, v170
	v_mov_b32_e32 v3, v171
	v_pk_mul_f32 v[2:3], v[34:35], v[2:3]
	v_pk_mul_f32 v[0:1], v[46:47], v[0:1]
	v_lshlrev_b32_e32 v34, 16, v44
	v_cvt_pk_bf16_f32 v0, v0, v1
	v_cvt_pk_bf16_f32 v1, v2, v3
	global_store_dwordx2 v[42:43], v[0:1], off offset:1536
	v_and_b32_e32 v35, 0xffff0000, v44
	v_lshlrev_b32_e32 v42, 16, v45
	v_and_b32_e32 v43, 0xffff0000, v45
	v_lshlrev_b32_e32 v45, 16, v52
	v_and_b32_e32 v47, 0xffff0000, v52
	v_mul_f32_e32 v44, v25, v25
	v_mul_f32_e32 v46, v27, v27
	v_mov_b32_e32 v53, v45
	v_mul_f32_e32 v52, v35, v35
	v_pk_fma_f32 v[64:65], v[24:25], v[24:25], v[44:45] op_sel_hi:[1,1,0]
	v_pk_fma_f32 v[66:67], v[26:27], v[26:27], v[46:47] op_sel_hi:[1,1,0]
	v_mul_f32_e32 v56, v43, v43
	v_pk_fma_f32 v[50:51], v[32:33], v[32:33], v[50:51]
	v_pk_fma_f32 v[68:69], v[34:35], v[34:35], v[52:53] op_sel_hi:[1,1,0]
	v_mov_b32_e32 v44, v66
	v_mov_b32_e32 v52, v64
	v_mul_f32_e32 v70, v47, v47
	v_pk_fma_f32 v[56:57], v[42:43], v[42:43], v[56:57] op_sel_hi:[1,1,0]
	v_pk_add_f32 v[64:65], v[66:67], v[64:65]
	v_pk_add_f32 v[50:51], v[50:51], v[50:51] op_sel:[0,1] op_sel_hi:[1,0]
	v_pk_mul_f32 v[52:53], v[44:45], v[52:53]
	v_mov_b32_e32 v69, v71
	v_mov_b32_e32 v57, v72
	v_mov_b32_e32 v51, v70
	v_mov_b32_e32 v65, v53
	v_pk_add_f32 v[56:57], v[68:69], v[56:57]
	v_pk_add_f32 v[50:51], v[64:65], v[50:51]
	s_nop 0
	v_pk_add_f32 v[50:51], v[50:51], v[56:57]
	s_nop 0
	v_add_f32_e32 v44, v50, v51
	ds_bpermute_b32 v46, v206, v44
	v_lshl_add_u64 v[50:51], v[22:23], 0, s[10:11]
	s_waitcnt lgkmcnt(0)
	v_add_f32_e32 v44, v44, v46
	ds_bpermute_b32 v46, v207, v44
	s_waitcnt lgkmcnt(0)
	v_add_f32_e32 v44, v44, v46
	ds_bpermute_b32 v46, v208, v44
	s_waitcnt lgkmcnt(0)
	v_add_f32_e32 v44, v44, v46
	ds_bpermute_b32 v46, v209, v44
	s_waitcnt lgkmcnt(0)
	v_add_f32_e32 v44, v44, v46
	ds_bpermute_b32 v46, v210, v44
	s_waitcnt lgkmcnt(0)
	v_add_f32_e32 v44, v44, v46
	ds_bpermute_b32 v46, v211, v44
	s_waitcnt lgkmcnt(0)
	v_add_f32_e32 v44, v44, v46
	v_fmamk_f32 v44, v44, 0x3a800000, v217
	v_rsq_f32_e32 v44, v44
	v_mov_b32_e32 v46, v45
	v_pk_mul_f32 v[26:27], v[44:45], v[26:27] op_sel_hi:[0,1]
	v_pk_mul_f32 v[24:25], v[44:45], v[24:25] op_sel_hi:[0,1]
	s_nop 0
	v_mov_b32_e32 v0, v156
	v_mov_b32_e32 v1, v157
	v_mov_b32_e32 v2, v158
	v_mov_b32_e32 v3, v159
	v_pk_mul_f32 v[2:3], v[24:25], v[2:3]
	v_pk_mul_f32 v[0:1], v[26:27], v[0:1]
	v_mov_b32_e32 v24, v32
	v_cvt_pk_bf16_f32 v0, v0, v1
	v_cvt_pk_bf16_f32 v1, v2, v3
	global_store_dwordx2 v[50:51], v[0:1], off
	v_mov_b32_e32 v25, v38
	v_mov_b32_e32 v38, v33
	v_pk_mul_f32 v[24:25], v[44:45], v[24:25] op_sel_hi:[0,1]
	v_pk_mul_f32 v[26:27], v[44:45], v[38:39] op_sel_hi:[0,1]
	v_pk_mul_f32 v[38:39], v[46:47], v[44:45] op_sel_hi:[1,0]
	v_and_b32_e32 v47, 0xffff0000, v54
	v_lshlrev_b32_e32 v33, 16, v61
	v_lshlrev_b32_e32 v32, 16, v60
	s_nop 0
	v_mov_b32_e32 v0, v160
	v_mov_b32_e32 v1, v161
	v_mov_b32_e32 v2, v162
	v_mov_b32_e32 v3, v163
	v_pk_mul_f32 v[2:3], v[26:27], v[2:3]
	v_pk_mul_f32 v[0:1], v[24:25], v[0:1]
	v_pk_mul_f32 v[24:25], v[44:45], v[34:35] op_sel_hi:[0,1]
	v_cvt_pk_bf16_f32 v0, v0, v1
	v_cvt_pk_bf16_f32 v1, v2, v3
	global_store_dwordx2 v[50:51], v[0:1], off offset:512
	v_pk_mul_f32 v[26:27], v[44:45], v[42:43] op_sel_hi:[0,1]
	v_pk_mul_f32 v[42:43], v[48:49], v[44:45] op_sel_hi:[1,0]
	v_and_b32_e32 v35, 0xffff0000, v61
	v_and_b32_e32 v34, 0xffff0000, v60
	v_lshlrev_b32_e32 v45, 16, v54
	v_mov_b32_e32 v53, v45
	v_lshlrev_b32_e32 v48, 16, v55
	v_and_b32_e32 v49, 0xffff0000, v55
	v_mul_f32_e32 v64, v49, v49
	s_nop 0
	v_mov_b32_e32 v0, v164
; DI unsigned cvt_pk_bf16(float lo, float hi) { const f32x2 v = {lo, hi}; return __builtin_bit_cast(unsigned, __builtin_convertvector(v, bf16x2_t)); }
; template <bool XOUT_BF, int NR>
; DI void norm_rows(const bf16_t* xin, const bf16_t* Rb, const float* gpost, void* xout, const float* gpre, bf16_t* xnb, size_t row0, size_t rstride, int lane) {
;     ...
;     if (xnb) {
; #pragma unroll
;         for (int o = 1; o < 64; o <<= 1)
; #pragma unroll
;             for (int q = 0; q < NR; ++q) s2[q] += __shfl_xor(s2[q], o);
; #pragma unroll
;         for (int q = 0; q < NR; ++q) { const float rinv = __builtin_amdgcn_rsqf(s2[q] * (1.f / 1024.f) + EPS);
; #pragma unroll
;             for (int j = 0; j < 4; ++j) { const size_t off = (row0 + q * rstride) * D + 4 * lane + 256 * j;
;                 const f32x4 g = *(const f32x4*)(gpre + 4 * lane + 256 * j); const f32x4 o = v[q][j] * rinv * g;
;                 u32x2 w; w.x = cvt_pk_bf16(o[0], o[1]); w.y = cvt_pk_bf16(o[2], o[3]); *(u32x2*)(xnb + off) = w; } }
	v_mov_b32_e32 v1, v165
	v_mov_b32_e32 v2, v166
	v_mov_b32_e32 v3, v167
	v_pk_mul_f32 v[2:3], v[26:27], v[2:3]
	v_pk_mul_f32 v[0:1], v[24:25], v[0:1]
	v_and_b32_e32 v25, 0xffff0000, v62
	v_cvt_pk_bf16_f32 v0, v0, v1
	v_cvt_pk_bf16_f32 v1, v2, v3
	global_store_dwordx2 v[50:51], v[0:1], off offset:1024
	v_and_b32_e32 v27, 0xffff0000, v63
	v_lshlrev_b32_e32 v24, 16, v62
	v_lshlrev_b32_e32 v26, 16, v63
	v_mul_f32_e32 v44, v27, v27
	v_mul_f32_e32 v46, v25, v25
	v_pk_fma_f32 v[56:57], v[26:27], v[26:27], v[44:45] op_sel_hi:[1,1,0]
	v_mul_f32_e32 v62, v47, v47
	v_mul_f32_e32 v63, v48, v48
	s_nop 0
	v_mov_b32_e32 v0, v168
	v_mov_b32_e32 v1, v169
	v_mov_b32_e32 v2, v170
	v_mov_b32_e32 v3, v171
	v_pk_mul_f32 v[2:3], v[42:43], v[2:3]
	v_pk_mul_f32 v[0:1], v[38:39], v[0:1]
	v_and_b32_e32 v39, 0xffff0000, v58
	v_cvt_pk_bf16_f32 v0, v0, v1
	v_cvt_pk_bf16_f32 v1, v2, v3
	global_store_dwordx2 v[50:51], v[0:1], off offset:1536
	v_lshlrev_b32_e32 v38, 16, v58
	v_lshlrev_b32_e32 v42, 16, v59
	v_and_b32_e32 v43, 0xffff0000, v59
	v_pk_mul_f32 v[50:51], v[34:35], v[34:35]
	v_mul_f32_e32 v52, v39, v39
	v_pk_fma_f32 v[58:59], v[24:25], v[24:25], v[46:47] op_sel_hi:[1,1,0]
	v_mul_f32_e32 v54, v43, v43
	v_pk_fma_f32 v[50:51], v[32:33], v[32:33], v[50:51]
	v_pk_fma_f32 v[60:61], v[38:39], v[38:39], v[52:53] op_sel_hi:[1,1,0]
	v_mov_b32_e32 v44, v58
	v_mov_b32_e32 v52, v56
	v_pk_fma_f32 v[54:55], v[42:43], v[42:43], v[54:55] op_sel_hi:[1,1,0]
	v_pk_add_f32 v[56:57], v[58:59], v[56:57]
	v_pk_add_f32 v[50:51], v[50:51], v[50:51] op_sel:[0,1] op_sel_hi:[1,0]
	v_pk_mul_f32 v[52:53], v[44:45], v[52:53]
	v_mov_b32_e32 v61, v63
	v_mov_b32_e32 v55, v64
	v_mov_b32_e32 v51, v62
	v_mov_b32_e32 v57, v53
	v_pk_add_f32 v[54:55], v[60:61], v[54:55]
	v_pk_add_f32 v[50:51], v[56:57], v[50:51]
	s_nop 0
	v_pk_add_f32 v[50:51], v[50:51], v[54:55]
	s_nop 0
	v_add_f32_e32 v44, v50, v51
	ds_bpermute_b32 v46, v206, v44
	v_lshl_add_u64 v[50:51], v[14:15], 0, s[10:11]
	s_waitcnt lgkmcnt(0)
	v_add_f32_e32 v44, v44, v46
	ds_bpermute_b32 v46, v207, v44
	s_waitcnt lgkmcnt(0)
	v_add_f32_e32 v44, v44, v46
	ds_bpermute_b32 v46, v208, v44
	s_waitcnt lgkmcnt(0)
	v_add_f32_e32 v44, v44, v46
	ds_bpermute_b32 v46, v209, v44
	s_waitcnt lgkmcnt(0)
	v_add_f32_e32 v44, v44, v46
	ds_bpermute_b32 v46, v210, v44
	s_waitcnt lgkmcnt(0)
	v_add_f32_e32 v44, v44, v46
	ds_bpermute_b32 v46, v211, v44
	s_waitcnt lgkmcnt(0)
; DI unsigned cvt_pk_bf16(float lo, float hi) { const f32x2 v = {lo, hi}; return __builtin_bit_cast(unsigned, __builtin_convertvector(v, bf16x2_t)); }
; template <bool XOUT_BF, int NR>
; DI void norm_rows(const bf16_t* xin, const bf16_t* Rb, const float* gpost, void* xout, const float* gpre, bf16_t* xnb, size_t row0, size_t rstride, int lane) {
;     ...
;     if (xnb) {
; #pragma unroll
;         for (int o = 1; o < 64; o <<= 1)
; #pragma unroll
;             for (int q = 0; q < NR; ++q) s2[q] += __shfl_xor(s2[q], o);
; #pragma unroll
;         for (int q = 0; q < NR; ++q) { const float rinv = __builtin_amdgcn_rsqf(s2[q] * (1.f / 1024.f) + EPS);
; #pragma unroll
;             for (int j = 0; j < 4; ++j) { const size_t off = (row0 + q * rstride) * D + 4 * lane + 256 * j;
;                 const f32x4 g = *(const f32x4*)(gpre + 4 * lane + 256 * j); const f32x4 o = v[q][j] * rinv * g;
;                 u32x2 w; w.x = cvt_pk_bf16(o[0], o[1]); w.y = cvt_pk_bf16(o[2], o[3]); *(u32x2*)(xnb + off) = w; } }
	v_add_f32_e32 v44, v44, v46
	v_fmamk_f32 v44, v44, 0x3a800000, v217
	v_rsq_f32_e32 v44, v44
	v_mov_b32_e32 v46, v45
	v_pk_mul_f32 v[24:25], v[44:45], v[24:25] op_sel_hi:[0,1]
	v_pk_mul_f32 v[26:27], v[44:45], v[26:27] op_sel_hi:[0,1]
	s_nop 0
	v_mov_b32_e32 v0, v156
	v_mov_b32_e32 v1, v157
	v_mov_b32_e32 v2, v158
	v_mov_b32_e32 v3, v159
	v_pk_mul_f32 v[2:3], v[26:27], v[2:3]
	v_pk_mul_f32 v[0:1], v[24:25], v[0:1]
	v_mov_b32_e32 v24, v32
	v_cvt_pk_bf16_f32 v0, v0, v1
	v_cvt_pk_bf16_f32 v1, v2, v3
	global_store_dwordx2 v[50:51], v[0:1], off
	v_mov_b32_e32 v25, v34
	v_mov_b32_e32 v34, v33
	v_pk_mul_f32 v[24:25], v[44:45], v[24:25] op_sel_hi:[0,1]
	v_pk_mul_f32 v[26:27], v[44:45], v[34:35] op_sel_hi:[0,1]
	v_lshlrev_b32_e32 v33, 16, v37
	v_and_b32_e32 v35, 0xffff0000, v37
	v_and_b32_e32 v34, 0xffff0000, v36
	v_and_b32_e32 v37, 0xffff0000, v30
	v_lshlrev_b32_e32 v32, 16, v36
	v_lshlrev_b32_e32 v36, 16, v30
	v_lshlrev_b32_e32 v30, 16, v31
	v_and_b32_e32 v31, 0xffff0000, v31
	s_nop 0
	v_mov_b32_e32 v0, v160
	v_mov_b32_e32 v1, v161
	v_mov_b32_e32 v2, v162
	v_mov_b32_e32 v3, v163
	v_pk_mul_f32 v[2:3], v[26:27], v[2:3]
	v_pk_mul_f32 v[0:1], v[24:25], v[0:1]
	v_pk_mul_f32 v[24:25], v[44:45], v[38:39] op_sel_hi:[0,1]
	v_cvt_pk_bf16_f32 v0, v0, v1
	v_cvt_pk_bf16_f32 v1, v2, v3
	global_store_dwordx2 v[50:51], v[0:1], off offset:512
	v_pk_mul_f32 v[26:27], v[44:45], v[42:43] op_sel_hi:[0,1]
	v_pk_mul_f32 v[38:39], v[46:47], v[44:45] op_sel_hi:[1,0]
	v_pk_mul_f32 v[42:43], v[34:35], v[34:35]
	v_mul_f32_e32 v46, v31, v31
	v_pk_fma_f32 v[42:43], v[32:33], v[32:33], v[42:43]
	v_pk_fma_f32 v[46:47], v[30:31], v[30:31], v[46:47] op_sel_hi:[1,1,0]
	v_pk_add_f32 v[42:43], v[42:43], v[42:43] op_sel:[0,1] op_sel_hi:[1,0]
	s_nop 0
	v_mov_b32_e32 v0, v164
	v_mov_b32_e32 v1, v165
	v_mov_b32_e32 v2, v166
	v_mov_b32_e32 v3, v167
	v_pk_mul_f32 v[2:3], v[26:27], v[2:3]
	v_pk_mul_f32 v[0:1], v[24:25], v[0:1]
	v_lshlrev_b32_e32 v24, 16, v40
	v_cvt_pk_bf16_f32 v0, v0, v1
	v_cvt_pk_bf16_f32 v1, v2, v3
	global_store_dwordx2 v[50:51], v[0:1], off offset:1024
	v_and_b32_e32 v25, 0xffff0000, v40
	v_lshlrev_b32_e32 v26, 16, v41
	v_and_b32_e32 v27, 0xffff0000, v41
	v_pk_mul_f32 v[40:41], v[48:49], v[44:45] op_sel_hi:[1,0]
	v_mul_f32_e32 v44, v37, v37
	s_nop 0
	v_mov_b32_e32 v0, v168
	v_mov_b32_e32 v1, v169
	v_mov_b32_e32 v2, v170
	v_mov_b32_e32 v3, v171
	v_pk_mul_f32 v[2:3], v[40:41], v[2:3]
	v_pk_mul_f32 v[0:1], v[38:39], v[0:1]
	v_lshlrev_b32_e32 v39, 16, v28
	v_cvt_pk_bf16_f32 v0, v0, v1
	v_cvt_pk_bf16_f32 v1, v2, v3
	global_store_dwordx2 v[50:51], v[0:1], off offset:1536
	v_and_b32_e32 v41, 0xffff0000, v28
	v_mul_f32_e32 v38, v27, v27
	v_mul_f32_e32 v40, v25, v25
	v_mov_b32_e32 v45, v39
	v_pk_fma_f32 v[48:49], v[26:27], v[26:27], v[38:39] op_sel_hi:[1,1,0]
	v_pk_fma_f32 v[50:51], v[24:25], v[24:25], v[40:41] op_sel_hi:[1,1,0]
	v_lshlrev_b32_e32 v28, 16, v29
	v_and_b32_e32 v29, 0xffff0000, v29
	v_pk_fma_f32 v[52:53], v[36:37], v[36:37], v[44:45] op_sel_hi:[1,1,0]
	v_mov_b32_e32 v38, v50
	v_mov_b32_e32 v44, v48
	v_mul_f32_e32 v54, v41, v41
	v_mul_f32_e32 v55, v28, v28
	v_mul_f32_e32 v56, v29, v29
	v_pk_add_f32 v[48:49], v[50:51], v[48:49]
	v_pk_mul_f32 v[44:45], v[38:39], v[44:45]
	v_mov_b32_e32 v53, v55
	v_mov_b32_e32 v47, v56
	v_mov_b32_e32 v43, v54
	v_mov_b32_e32 v49, v45
	v_pk_add_f32 v[46:47], v[52:53], v[46:47]
	v_pk_add_f32 v[42:43], v[48:49], v[42:43]
	s_nop 0
	v_pk_add_f32 v[42:43], v[42:43], v[46:47]
	s_nop 0
	v_add_f32_e32 v38, v42, v43
	ds_bpermute_b32 v40, v206, v38
	v_lshl_add_u64 v[42:43], v[20:21], 0, s[10:11]
	s_waitcnt lgkmcnt(0)
	v_add_f32_e32 v38, v38, v40
	ds_bpermute_b32 v40, v207, v38
	s_waitcnt lgkmcnt(0)
	v_add_f32_e32 v38, v38, v40
	ds_bpermute_b32 v40, v208, v38
	s_waitcnt lgkmcnt(0)
	v_add_f32_e32 v38, v38, v40
	ds_bpermute_b32 v40, v209, v38
	s_waitcnt lgkmcnt(0)
	v_add_f32_e32 v38, v38, v40
	ds_bpermute_b32 v40, v210, v38
	s_waitcnt lgkmcnt(0)
	v_add_f32_e32 v38, v38, v40
	ds_bpermute_b32 v40, v211, v38
	s_waitcnt lgkmcnt(0)
	v_add_f32_e32 v38, v38, v40
	v_fmamk_f32 v38, v38, 0x3a800000, v217
	v_rsq_f32_e32 v38, v38
	v_mov_b32_e32 v40, v39
	v_pk_mul_f32 v[24:25], v[38:39], v[24:25] op_sel_hi:[0,1]
	v_pk_mul_f32 v[26:27], v[38:39], v[26:27] op_sel_hi:[0,1]
	s_nop 0
	v_mov_b32_e32 v0, v156
	v_mov_b32_e32 v1, v157
	v_mov_b32_e32 v2, v158
	v_mov_b32_e32 v3, v159
	v_pk_mul_f32 v[2:3], v[26:27], v[2:3]
	v_pk_mul_f32 v[0:1], v[24:25], v[0:1]
	v_mov_b32_e32 v24, v32
	v_cvt_pk_bf16_f32 v0, v0, v1
	v_cvt_pk_bf16_f32 v1, v2, v3
	global_store_dwordx2 v[42:43], v[0:1], off
	v_mov_b32_e32 v25, v34
	v_mov_b32_e32 v34, v33
	v_pk_mul_f32 v[24:25], v[38:39], v[24:25] op_sel_hi:[0,1]
	v_pk_mul_f32 v[26:27], v[38:39], v[34:35] op_sel_hi:[0,1]
	s_nop 0
	v_mov_b32_e32 v0, v160
	v_mov_b32_e32 v1, v161
	v_mov_b32_e32 v2, v162
	v_mov_b32_e32 v3, v163
	v_pk_mul_f32 v[2:3], v[26:27], v[2:3]
	v_pk_mul_f32 v[0:1], v[24:25], v[0:1]
	v_pk_mul_f32 v[24:25], v[38:39], v[36:37] op_sel_hi:[0,1]
	v_cvt_pk_bf16_f32 v0, v0, v1
	v_cvt_pk_bf16_f32 v1, v2, v3
	global_store_dwordx2 v[42:43], v[0:1], off offset:512
	v_pk_mul_f32 v[26:27], v[38:39], v[30:31] op_sel_hi:[0,1]
	s_nop 0
	v_mov_b32_e32 v0, v164
	v_mov_b32_e32 v1, v165
	v_mov_b32_e32 v2, v166
	v_mov_b32_e32 v3, v167
	v_pk_mul_f32 v[2:3], v[26:27], v[2:3]
	v_pk_mul_f32 v[0:1], v[24:25], v[0:1]
	v_pk_mul_f32 v[24:25], v[40:41], v[38:39] op_sel_hi:[1,0]
	v_cvt_pk_bf16_f32 v0, v0, v1
	v_cvt_pk_bf16_f32 v1, v2, v3
	global_store_dwordx2 v[42:43], v[0:1], off offset:1024
	v_pk_mul_f32 v[26:27], v[28:29], v[38:39] op_sel_hi:[1,0]
	s_nop 0
	v_mov_b32_e32 v0, v168
	v_mov_b32_e32 v1, v169
	v_mov_b32_e32 v2, v170
	v_mov_b32_e32 v3, v171
	v_pk_mul_f32 v[0:1], v[24:25], v[0:1]
	v_pk_mul_f32 v[2:3], v[26:27], v[2:3]
	v_cvt_pk_bf16_f32 v0, v0, v1
	v_cvt_pk_bf16_f32 v1, v2, v3
	global_store_dwordx2 v[42:43], v[0:1], off offset:1536
	s_branch .LBB0_1367
